# v054 + grid-barrier census (first barrier of each workgroup): the 16 agent-scope counter loads issued together and waited once instead of 16 serial round trips
# speedup vs baseline: 1.0023x; 1.0023x over previous
; __device__ __forceinline__ unsigned xb_ld(unsigned* p)              { return __hip_atomic_load(p, __ATOMIC_RELAXED, __HIP_MEMORY_SCOPE_AGENT); }
; __device__ __forceinline__ void xcd_barrier_complete(unsigned* bar, unsigned x, unsigned& nloc, unsigned& nx) {
;     const unsigned G = gridDim.x * gridDim.y * gridDim.z;
;     unsigned sum, cnt, mine, sp = 0u;
;     for (;;) {
;         sum = 0u; cnt = 0u; mine = 0u;
; #pragma unroll
;         for (unsigned j = 0; j < 16; ++j) { const unsigned c = xb_ld(&bar[XB_XCNT(j)]); sum += c; cnt += (c > 0u) ? 1u : 0u; mine = (j == x) ? c : mine; }
;         if (sum == G) break;
;         __builtin_amdgcn_s_sleep(1);
;         if ((++sp & 255u) == 0u) { if (xb_ld(&bar[XB_TMO])) break; if (sp > XB_SPIN_CAP) { atomicAdd(&bar[XB_TMO], 1u); break; } }
;     }
;     nloc = mine > 0u ? mine : 1u; nx = cnt > 0u ? cnt : 1u;
; }
.LBB0_125:
	v_readlane_b32 s6, v250, 10
	v_readlane_b32 s7, v250, 11
	global_load_dword v2, v17, s[26:27] sc1
	global_load_dword v1, v17, s[24:25] sc1
	s_mov_b64 s[8:9], -1
	s_nop 4
	global_load_dword v3, v17, s[6:7] sc1
	v_readlane_b32 s6, v250, 12
	v_readlane_b32 s7, v250, 13
	s_nop 4
	global_load_dword v4, v17, s[6:7] sc1
	v_readlane_b32 s6, v250, 14
	v_readlane_b32 s7, v250, 15
	s_nop 4
	global_load_dword v5, v17, s[6:7] sc1
	v_readlane_b32 s6, v250, 16
	v_readlane_b32 s7, v250, 17
	s_nop 4
	global_load_dword v6, v17, s[6:7] sc1
	v_readlane_b32 s6, v250, 18
	v_readlane_b32 s7, v250, 19
	s_nop 4
	global_load_dword v7, v17, s[6:7] sc1
	v_readlane_b32 s6, v250, 20
	v_readlane_b32 s7, v250, 21
	s_nop 4
	global_load_dword v8, v17, s[6:7] sc1
	v_readlane_b32 s6, v250, 22
	v_readlane_b32 s7, v250, 23
	s_nop 4
	global_load_dword v9, v17, s[6:7] sc1
	v_readlane_b32 s6, v250, 24
	v_readlane_b32 s7, v250, 25
	s_nop 4
	global_load_dword v10, v17, s[6:7] sc1
	v_readlane_b32 s6, v250, 26
	v_readlane_b32 s7, v250, 27
	s_nop 4
	global_load_dword v11, v17, s[6:7] sc1
	v_readlane_b32 s6, v250, 28
	v_readlane_b32 s7, v250, 29
	s_nop 4
	global_load_dword v12, v17, s[6:7] sc1
	v_readlane_b32 s6, v250, 30
	v_readlane_b32 s7, v250, 31
	s_nop 4
	global_load_dword v13, v17, s[6:7] sc1
	v_readlane_b32 s6, v250, 32
	v_readlane_b32 s7, v250, 33
	s_nop 4
	global_load_dword v14, v17, s[6:7] sc1
	v_readlane_b32 s6, v250, 34
	v_readlane_b32 s7, v250, 35
	s_nop 4
	global_load_dword v15, v17, s[6:7] sc1
	v_readlane_b32 s6, v250, 36
	v_readlane_b32 s7, v250, 37
	s_nop 4
	global_load_dword v16, v17, s[6:7] sc1
	s_mov_b64 s[6:7], -1
	s_waitcnt vmcnt(0)
	v_add_u32_e32 v18, v1, v2
	v_add_u32_e32 v18, v18, v3
	v_add_u32_e32 v18, v18, v4
	v_add_u32_e32 v18, v18, v5
	v_add_u32_e32 v18, v18, v6
	v_add_u32_e32 v18, v18, v7
	v_add_u32_e32 v18, v18, v8
	v_add_u32_e32 v18, v18, v9
	v_add_u32_e32 v18, v18, v10
	v_add_u32_e32 v18, v18, v11
	v_add_u32_e32 v18, v18, v12
	v_add_u32_e32 v18, v18, v13
	v_add_u32_e32 v18, v18, v14
	v_add_u32_e32 v18, v18, v15
	v_add_u32_e32 v18, v18, v16
	v_cmp_eq_u32_e32 vcc, s1, v18
	s_cbranch_vccnz .LBB0_124
	s_and_b32 s6, s0, 0xff
	s_cmp_eq_u32 s6, 0
	s_mov_b64 s[6:7], -1
	s_mov_b64 s[10:11], -1
	s_sleep 1
	s_cbranch_scc0 .LBB0_129
	global_load_dword v18, v17, s[22:23] sc1
	s_waitcnt vmcnt(0)
	v_cmp_eq_u32_e32 vcc, 0, v18
	s_cbranch_vccnz .LBB0_131
	s_mov_b64 s[10:11], 0

; __device__ __forceinline__ unsigned xb_ld(unsigned* p)              { return __hip_atomic_load(p, __ATOMIC_RELAXED, __HIP_MEMORY_SCOPE_AGENT); }
; __device__ __forceinline__ void xcd_barrier_complete(unsigned* bar, unsigned x, unsigned& nloc, unsigned& nx) {
;     const unsigned G = gridDim.x * gridDim.y * gridDim.z;
;     unsigned sum, cnt, mine, sp = 0u;
;     for (;;) {
;         sum = 0u; cnt = 0u; mine = 0u;
; #pragma unroll
;         for (unsigned j = 0; j < 16; ++j) { const unsigned c = xb_ld(&bar[XB_XCNT(j)]); sum += c; cnt += (c > 0u) ? 1u : 0u; mine = (j == x) ? c : mine; }
;         if (sum == G) break;
;         __builtin_amdgcn_s_sleep(1);
;         if ((++sp & 255u) == 0u) { if (xb_ld(&bar[XB_TMO])) break; if (sp > XB_SPIN_CAP) { atomicAdd(&bar[XB_TMO], 1u); break; } }
;     }
;     nloc = mine > 0u ? mine : 1u; nx = cnt > 0u ? cnt : 1u;
; }
.LBB0_211:
	v_readlane_b32 s2, v250, 10
	v_readlane_b32 s3, v250, 11
	global_load_dword v2, v98, s[26:27] sc1
	global_load_dword v1, v98, s[24:25] sc1
	s_mov_b64 s[6:7], -1
	s_mov_b64 s[8:9], -1
	s_nop 4
	global_load_dword v3, v98, s[2:3] sc1
	v_readlane_b32 s2, v250, 12
	v_readlane_b32 s3, v250, 13
	s_nop 4
	global_load_dword v4, v98, s[2:3] sc1
	v_readlane_b32 s2, v250, 14
	v_readlane_b32 s3, v250, 15
	s_nop 4
	global_load_dword v5, v98, s[2:3] sc1
	v_readlane_b32 s2, v250, 16
	v_readlane_b32 s3, v250, 17
	s_nop 4
	global_load_dword v6, v98, s[2:3] sc1
	v_readlane_b32 s2, v250, 18
	v_readlane_b32 s3, v250, 19
	s_nop 4
	global_load_dword v7, v98, s[2:3] sc1
	v_readlane_b32 s2, v250, 20
	v_readlane_b32 s3, v250, 21
	s_nop 4
	global_load_dword v8, v98, s[2:3] sc1
	v_readlane_b32 s2, v250, 22
	v_readlane_b32 s3, v250, 23
	s_nop 4
	global_load_dword v9, v98, s[2:3] sc1
	v_readlane_b32 s2, v250, 24
	v_readlane_b32 s3, v250, 25
	s_nop 4
	global_load_dword v10, v98, s[2:3] sc1
	v_readlane_b32 s2, v250, 26
	v_readlane_b32 s3, v250, 27
	s_nop 4
	global_load_dword v11, v98, s[2:3] sc1
	v_readlane_b32 s2, v250, 28
	v_readlane_b32 s3, v250, 29
	s_nop 4
	global_load_dword v12, v98, s[2:3] sc1
	v_readlane_b32 s2, v250, 30
	v_readlane_b32 s3, v250, 31
	s_nop 4
	global_load_dword v13, v98, s[2:3] sc1
	v_readlane_b32 s2, v250, 32
	v_readlane_b32 s3, v250, 33
	s_nop 4
	global_load_dword v14, v98, s[2:3] sc1
	v_readlane_b32 s2, v250, 34
	v_readlane_b32 s3, v250, 35
	s_nop 4
	global_load_dword v15, v98, s[2:3] sc1
	v_readlane_b32 s2, v250, 36
	v_readlane_b32 s3, v250, 37
	s_nop 4
	global_load_dword v16, v98, s[2:3] sc1
	s_waitcnt vmcnt(0)
	v_add_u32_e32 v17, v1, v2
	v_add_u32_e32 v17, v17, v3
	v_add_u32_e32 v17, v17, v4
	v_add_u32_e32 v17, v17, v5
	v_add_u32_e32 v17, v17, v6
	v_add_u32_e32 v17, v17, v7
	v_add_u32_e32 v17, v17, v8
	v_add_u32_e32 v17, v17, v9
	v_add_u32_e32 v17, v17, v10
	v_add_u32_e32 v17, v17, v11
	v_add_u32_e32 v17, v17, v12
	v_add_u32_e32 v17, v17, v13
	v_add_u32_e32 v17, v17, v14
	v_add_u32_e32 v17, v17, v15
	v_add_u32_e32 v17, v17, v16
	v_cmp_eq_u32_e32 vcc, s0, v17
	s_cbranch_vccnz .LBB0_210
	s_and_b32 s6, s1, 0xff
	s_cmp_eq_u32 s6, 0
	s_mov_b64 s[6:7], -1
	s_mov_b64 s[10:11], -1
	s_sleep 1
	s_cbranch_scc0 .LBB0_215
	global_load_dword v17, v98, s[22:23] sc1
	s_waitcnt vmcnt(0)
	v_cmp_eq_u32_e32 vcc, 0, v17
	s_cbranch_vccnz .LBB0_217
	s_mov_b64 s[10:11], 0

; __device__ __forceinline__ unsigned xb_ld(unsigned* p)              { return __hip_atomic_load(p, __ATOMIC_RELAXED, __HIP_MEMORY_SCOPE_AGENT); }
; __device__ __forceinline__ void xcd_barrier_complete(unsigned* bar, unsigned x, unsigned& nloc, unsigned& nx) {
;     const unsigned G = gridDim.x * gridDim.y * gridDim.z;
;     unsigned sum, cnt, mine, sp = 0u;
;     for (;;) {
;         sum = 0u; cnt = 0u; mine = 0u;
; #pragma unroll
;         for (unsigned j = 0; j < 16; ++j) { const unsigned c = xb_ld(&bar[XB_XCNT(j)]); sum += c; cnt += (c > 0u) ? 1u : 0u; mine = (j == x) ? c : mine; }
;         if (sum == G) break;
;         __builtin_amdgcn_s_sleep(1);
;         if ((++sp & 255u) == 0u) { if (xb_ld(&bar[XB_TMO])) break; if (sp > XB_SPIN_CAP) { atomicAdd(&bar[XB_TMO], 1u); break; } }
;     }
;     nloc = mine > 0u ? mine : 1u; nx = cnt > 0u ? cnt : 1u;
; }
.LBB0_692:
	v_readlane_b32 s2, v250, 10
	v_readlane_b32 s3, v250, 11
	global_load_dword v2, v98, s[26:27] sc1
	global_load_dword v1, v98, s[24:25] sc1
	s_mov_b64 s[6:7], -1
	s_mov_b64 s[8:9], -1
	s_nop 4
	global_load_dword v3, v98, s[2:3] sc1
	v_readlane_b32 s2, v250, 12
	v_readlane_b32 s3, v250, 13
	s_nop 4
	global_load_dword v4, v98, s[2:3] sc1
	v_readlane_b32 s2, v250, 14
	v_readlane_b32 s3, v250, 15
	s_nop 4
	global_load_dword v5, v98, s[2:3] sc1
	v_readlane_b32 s2, v250, 16
	v_readlane_b32 s3, v250, 17
	s_nop 4
	global_load_dword v6, v98, s[2:3] sc1
	v_readlane_b32 s2, v250, 18
	v_readlane_b32 s3, v250, 19
	s_nop 4
	global_load_dword v7, v98, s[2:3] sc1
	v_readlane_b32 s2, v250, 20
	v_readlane_b32 s3, v250, 21
	s_nop 4
	global_load_dword v8, v98, s[2:3] sc1
	v_readlane_b32 s2, v250, 22
	v_readlane_b32 s3, v250, 23
	s_nop 4
	global_load_dword v9, v98, s[2:3] sc1
	v_readlane_b32 s2, v250, 24
	v_readlane_b32 s3, v250, 25
	s_nop 4
	global_load_dword v10, v98, s[2:3] sc1
	v_readlane_b32 s2, v250, 26
	v_readlane_b32 s3, v250, 27
	s_nop 4
	global_load_dword v11, v98, s[2:3] sc1
	v_readlane_b32 s2, v250, 28
	v_readlane_b32 s3, v250, 29
	s_nop 4
	global_load_dword v12, v98, s[2:3] sc1
	v_readlane_b32 s2, v250, 30
	v_readlane_b32 s3, v250, 31
	s_nop 4
	global_load_dword v13, v98, s[2:3] sc1
	v_readlane_b32 s2, v250, 32
	v_readlane_b32 s3, v250, 33
	s_nop 4
	global_load_dword v14, v98, s[2:3] sc1
	v_readlane_b32 s2, v250, 34
	v_readlane_b32 s3, v250, 35
	s_nop 4
	global_load_dword v15, v98, s[2:3] sc1
	v_readlane_b32 s2, v250, 36
	v_readlane_b32 s3, v250, 37
	s_nop 4
	global_load_dword v16, v98, s[2:3] sc1
	s_waitcnt vmcnt(0)
	v_add_u32_e32 v17, v1, v2
	v_add_u32_e32 v17, v17, v3
	v_add_u32_e32 v17, v17, v4
	v_add_u32_e32 v17, v17, v5
	v_add_u32_e32 v17, v17, v6
	v_add_u32_e32 v17, v17, v7
	v_add_u32_e32 v17, v17, v8
	v_add_u32_e32 v17, v17, v9
	v_add_u32_e32 v17, v17, v10
	v_add_u32_e32 v17, v17, v11
	v_add_u32_e32 v17, v17, v12
	v_add_u32_e32 v17, v17, v13
	v_add_u32_e32 v17, v17, v14
	v_add_u32_e32 v17, v17, v15
	v_add_u32_e32 v17, v17, v16
	v_cmp_eq_u32_e32 vcc, s0, v17
	s_cbranch_vccnz .LBB0_691
	s_and_b32 s2, s1, 0xff
	s_cmp_eq_u32 s2, 0
	s_mov_b64 s[10:11], -1
	s_sleep 1
	s_cbranch_scc0 .LBB0_696
	global_load_dword v17, v98, s[22:23] sc1
	s_waitcnt vmcnt(0)
	v_cmp_eq_u32_e32 vcc, 0, v17
	s_cbranch_vccnz .LBB0_698
	s_mov_b64 s[10:11], 0
